# v59 + kt_tile main loop software-pipelined (LDS fragment reads of step k+1 under the FMAs of step k)
# speedup vs baseline: 1.0047x; 1.0047x over previous
.LBB0_564:
	s_waitcnt vmcnt(0)
	v_mov_b32_e32 v34, v208
	s_lshl_b32 s8, s13, 3
	s_and_b32 s8, s8, 0xffffff80
	s_load_dwordx2 s[14:15], s[0:1], 0x80
	v_and_b32_e32 v84, 15, v34
	v_ashrrev_i32_e32 v85, 4, v34
	v_lshlrev_b32_e32 v0, 4, v84
	v_lshl_add_u64 v[6:7], s[6:7], 0, v[0:1]
	v_add_u32_e32 v2, s8, v85
	v_mov_b32_e32 v3, 0
	v_lshlrev_b64 v[2:3], 8, v[2:3]
	v_lshl_add_u64 v[2:3], v[6:7], 0, v[2:3]
	global_load_dwordx4 v[52:55], v[2:3], off
	v_add_co_u32_e32 v2, vcc, 0x2000, v2
	s_nop 1
	v_addc_co_u32_e32 v3, vcc, 0, v3, vcc
	global_load_dwordx4 v[56:59], v[2:3], off
	v_add_co_u32_e32 v2, vcc, 0x2000, v2
	s_nop 1
	v_addc_co_u32_e32 v3, vcc, 0, v3, vcc
	global_load_dwordx4 v[60:63], v[2:3], off
	v_add_co_u32_e32 v2, vcc, 0x2000, v2
	s_nop 1
	v_addc_co_u32_e32 v3, vcc, 0, v3, vcc
	global_load_dwordx4 v[64:67], v[2:3], off
	s_lshl_b32 s9, s13, 7
	s_and_b32 s9, s9, 0x780
	v_and_b32_e32 v86, 31, v34
	v_lshlrev_b32_e32 v0, 4, v86
	s_waitcnt lgkmcnt(0)
	s_add_u32 s14, s14, s2
	s_addc_u32 s15, s15, s3
	s_lshl_b32 s16, s9, 2
	s_add_u32 s14, s14, s16
	s_addc_u32 s15, s15, 0
	v_lshl_add_u64 v[8:9], s[14:15], 0, v[0:1]
	v_ashrrev_i32_e32 v2, 5, v34
	v_mov_b32_e32 v3, 0
	v_lshlrev_b64 v[2:3], 13, v[2:3]
	v_lshl_add_u64 v[2:3], v[8:9], 0, v[2:3]
	global_load_dwordx4 v[68:71], v[2:3], off
	v_add_co_u32_e32 v2, vcc, 0x20000, v2
	s_nop 1
	v_addc_co_u32_e32 v3, vcc, 0, v3, vcc
	global_load_dwordx4 v[72:75], v[2:3], off
	v_add_co_u32_e32 v2, vcc, 0x20000, v2
	s_nop 1
	v_addc_co_u32_e32 v3, vcc, 0, v3, vcc
	global_load_dwordx4 v[76:79], v[2:3], off
	v_add_co_u32_e32 v2, vcc, 0x20000, v2
	s_nop 1
	v_addc_co_u32_e32 v3, vcc, 0, v3, vcc
	global_load_dwordx4 v[80:83], v[2:3], off
	v_mul_u32_u24_e32 v87, 0x840, v84
	v_lshl_add_u32 v87, v85, 2, v87
	v_add_u32_e32 v88, 0x400, v87
	v_ashrrev_i32_e32 v89, 5, v34
	v_lshlrev_b32_e32 v89, 9, v89
	v_lshl_add_u32 v89, v86, 4, v89
	s_waitcnt vmcnt(7)
	ds_write2_b32 v87, v52, v53 offset0:0 offset1:132
	ds_write2_b32 v88, v54, v55 offset0:8 offset1:140
	s_waitcnt vmcnt(6)
	ds_write2_b32 v87, v56, v57 offset0:32 offset1:164
	ds_write2_b32 v88, v58, v59 offset0:40 offset1:172
	s_waitcnt vmcnt(5)
	ds_write2_b32 v87, v60, v61 offset0:64 offset1:196
	ds_write2_b32 v88, v62, v63 offset0:72 offset1:204
	s_waitcnt vmcnt(4)
	ds_write2_b32 v87, v64, v65 offset0:96 offset1:228
	ds_write2_b32 v88, v66, v67 offset0:104 offset1:236
	s_waitcnt vmcnt(3)
	ds_write_b128 v89, v[68:71] offset:34816
	s_waitcnt vmcnt(2)
	ds_write_b128 v89, v[72:75] offset:43008
	s_waitcnt vmcnt(1)
	ds_write_b128 v89, v[76:79] offset:51200
	s_waitcnt vmcnt(0)
	ds_write_b128 v89, v[80:83] offset:59392
	s_add_i32 s14, 0, 0x8800
	v_and_b32_e32 v2, 0xffffffe0, v34
	v_and_b32_e32 v0, 31, v34
	v_add_u32_e32 v36, s14, v2
	v_mov_b32_e32 v2, 0
	v_lshl_add_u32 v35, v0, 4, 0
	s_mov_b32 s14, 0
	v_mov_b32_e32 v3, v2
	v_mov_b32_e32 v4, v2
	v_mov_b32_e32 v5, v2
	v_mov_b32_e32 v30, v2
	v_mov_b32_e32 v31, v2
	v_mov_b32_e32 v32, v2
	v_mov_b32_e32 v33, v2
	v_mov_b32_e32 v26, v2
	v_mov_b32_e32 v27, v2
	v_mov_b32_e32 v28, v2
	v_mov_b32_e32 v29, v2
	v_mov_b32_e32 v22, v2
	v_mov_b32_e32 v23, v2
	v_mov_b32_e32 v24, v2
	v_mov_b32_e32 v25, v2
	v_mov_b32_e32 v18, v2
	v_mov_b32_e32 v19, v2
	v_mov_b32_e32 v20, v2
	v_mov_b32_e32 v21, v2
	v_mov_b32_e32 v14, v2
	v_mov_b32_e32 v15, v2
	v_mov_b32_e32 v16, v2
	v_mov_b32_e32 v17, v2
	v_mov_b32_e32 v10, v2
	v_mov_b32_e32 v11, v2
	v_mov_b32_e32 v12, v2
	v_mov_b32_e32 v13, v2
	v_mov_b32_e32 v6, v2
	v_mov_b32_e32 v7, v2
	v_mov_b32_e32 v8, v2
	v_mov_b32_e32 v9, v2
	s_waitcnt lgkmcnt(0)
	s_barrier
	v_add_u32_e32 v37, s14, v36
	ds_read_b128 v[38:41], v35
	ds_read_b128 v[42:45], v37
	ds_read_b128 v[46:49], v37 offset:16
.LBB0_565:
	v_add_u32_e32 v37, s14, v36
	ds_read_b128 v[52:55], v35 offset:528
	ds_read_b128 v[56:59], v37 offset:512
	ds_read_b128 v[60:63], v37 offset:528
	s_waitcnt lgkmcnt(3)
	v_pk_fma_f32 v[32:33], v[40:41], v[42:43], v[32:33] op_sel_hi:[1,0,1]
	v_pk_fma_f32 v[30:31], v[38:39], v[42:43], v[30:31] op_sel_hi:[1,0,1]
	v_pk_fma_f32 v[28:29], v[40:41], v[42:43], v[28:29] op_sel:[0,1,0]
	v_pk_fma_f32 v[26:27], v[38:39], v[42:43], v[26:27] op_sel:[0,1,0]
	v_pk_fma_f32 v[24:25], v[40:41], v[44:45], v[24:25] op_sel_hi:[1,0,1]
	v_pk_fma_f32 v[22:23], v[38:39], v[44:45], v[22:23] op_sel_hi:[1,0,1]
	v_pk_fma_f32 v[20:21], v[40:41], v[44:45], v[20:21] op_sel:[0,1,0]
	v_pk_fma_f32 v[18:19], v[38:39], v[44:45], v[18:19] op_sel:[0,1,0]
	v_pk_fma_f32 v[16:17], v[40:41], v[46:47], v[16:17] op_sel_hi:[1,0,1]
	v_pk_fma_f32 v[14:15], v[38:39], v[46:47], v[14:15] op_sel_hi:[1,0,1]
	v_pk_fma_f32 v[12:13], v[40:41], v[46:47], v[12:13] op_sel:[0,1,0]
	v_pk_fma_f32 v[10:11], v[38:39], v[46:47], v[10:11] op_sel:[0,1,0]
	v_pk_fma_f32 v[8:9], v[40:41], v[48:49], v[8:9] op_sel_hi:[1,0,1]
	v_pk_fma_f32 v[6:7], v[38:39], v[48:49], v[6:7] op_sel_hi:[1,0,1]
	v_pk_fma_f32 v[4:5], v[40:41], v[48:49], v[4:5] op_sel:[0,1,0]
	v_pk_fma_f32 v[2:3], v[38:39], v[48:49], v[2:3] op_sel:[0,1,0]
	ds_read_b128 v[38:41], v35 offset:1056
	ds_read_b128 v[42:45], v37 offset:1024
	ds_read_b128 v[46:49], v37 offset:1040
	s_waitcnt lgkmcnt(3)
	v_pk_fma_f32 v[32:33], v[54:55], v[56:57], v[32:33] op_sel_hi:[1,0,1]
	v_pk_fma_f32 v[30:31], v[52:53], v[56:57], v[30:31] op_sel_hi:[1,0,1]
	v_pk_fma_f32 v[28:29], v[54:55], v[56:57], v[28:29] op_sel:[0,1,0]
	v_pk_fma_f32 v[26:27], v[52:53], v[56:57], v[26:27] op_sel:[0,1,0]
	v_pk_fma_f32 v[24:25], v[54:55], v[58:59], v[24:25] op_sel_hi:[1,0,1]
	v_pk_fma_f32 v[22:23], v[52:53], v[58:59], v[22:23] op_sel_hi:[1,0,1]
	v_pk_fma_f32 v[20:21], v[54:55], v[58:59], v[20:21] op_sel:[0,1,0]
	v_pk_fma_f32 v[18:19], v[52:53], v[58:59], v[18:19] op_sel:[0,1,0]
	v_pk_fma_f32 v[16:17], v[54:55], v[60:61], v[16:17] op_sel_hi:[1,0,1]
	v_pk_fma_f32 v[14:15], v[52:53], v[60:61], v[14:15] op_sel_hi:[1,0,1]
	v_pk_fma_f32 v[12:13], v[54:55], v[60:61], v[12:13] op_sel:[0,1,0]
	v_pk_fma_f32 v[10:11], v[52:53], v[60:61], v[10:11] op_sel:[0,1,0]
	v_pk_fma_f32 v[8:9], v[54:55], v[62:63], v[8:9] op_sel_hi:[1,0,1]
	v_pk_fma_f32 v[6:7], v[52:53], v[62:63], v[6:7] op_sel_hi:[1,0,1]
	v_pk_fma_f32 v[4:5], v[54:55], v[62:63], v[4:5] op_sel:[0,1,0]
	v_pk_fma_f32 v[2:3], v[52:53], v[62:63], v[2:3] op_sel:[0,1,0]
	ds_read_b128 v[52:55], v35 offset:1584
	ds_read_b128 v[56:59], v37 offset:1536
	ds_read_b128 v[60:63], v37 offset:1552
	s_waitcnt lgkmcnt(3)
	v_pk_fma_f32 v[32:33], v[40:41], v[42:43], v[32:33] op_sel_hi:[1,0,1]
	v_pk_fma_f32 v[30:31], v[38:39], v[42:43], v[30:31] op_sel_hi:[1,0,1]
	v_pk_fma_f32 v[28:29], v[40:41], v[42:43], v[28:29] op_sel:[0,1,0]
	v_pk_fma_f32 v[26:27], v[38:39], v[42:43], v[26:27] op_sel:[0,1,0]
	v_pk_fma_f32 v[24:25], v[40:41], v[44:45], v[24:25] op_sel_hi:[1,0,1]
	v_pk_fma_f32 v[22:23], v[38:39], v[44:45], v[22:23] op_sel_hi:[1,0,1]
	v_pk_fma_f32 v[20:21], v[40:41], v[44:45], v[20:21] op_sel:[0,1,0]
	v_pk_fma_f32 v[18:19], v[38:39], v[44:45], v[18:19] op_sel:[0,1,0]
	v_pk_fma_f32 v[16:17], v[40:41], v[46:47], v[16:17] op_sel_hi:[1,0,1]
	v_pk_fma_f32 v[14:15], v[38:39], v[46:47], v[14:15] op_sel_hi:[1,0,1]
	v_pk_fma_f32 v[12:13], v[40:41], v[46:47], v[12:13] op_sel:[0,1,0]
	v_pk_fma_f32 v[10:11], v[38:39], v[46:47], v[10:11] op_sel:[0,1,0]
	v_pk_fma_f32 v[8:9], v[40:41], v[48:49], v[8:9] op_sel_hi:[1,0,1]
	v_pk_fma_f32 v[6:7], v[38:39], v[48:49], v[6:7] op_sel_hi:[1,0,1]
	v_pk_fma_f32 v[4:5], v[40:41], v[48:49], v[4:5] op_sel:[0,1,0]
	v_pk_fma_f32 v[2:3], v[38:39], v[48:49], v[2:3] op_sel:[0,1,0]
	ds_read_b128 v[38:41], v35 offset:2112
	ds_read_b128 v[42:45], v37 offset:2048
	ds_read_b128 v[46:49], v37 offset:2064
	s_addk_i32 s14, 0x800
	s_cmpk_lg_u32 s14, 0x8000
	s_waitcnt lgkmcnt(3)
	v_pk_fma_f32 v[32:33], v[54:55], v[56:57], v[32:33] op_sel_hi:[1,0,1]
	v_pk_fma_f32 v[30:31], v[52:53], v[56:57], v[30:31] op_sel_hi:[1,0,1]
	v_pk_fma_f32 v[28:29], v[54:55], v[56:57], v[28:29] op_sel:[0,1,0]
	v_pk_fma_f32 v[26:27], v[52:53], v[56:57], v[26:27] op_sel:[0,1,0]
	v_pk_fma_f32 v[24:25], v[54:55], v[58:59], v[24:25] op_sel_hi:[1,0,1]
	v_pk_fma_f32 v[22:23], v[52:53], v[58:59], v[22:23] op_sel_hi:[1,0,1]
	v_pk_fma_f32 v[20:21], v[54:55], v[58:59], v[20:21] op_sel:[0,1,0]
	v_pk_fma_f32 v[18:19], v[52:53], v[58:59], v[18:19] op_sel:[0,1,0]
	v_pk_fma_f32 v[16:17], v[54:55], v[60:61], v[16:17] op_sel_hi:[1,0,1]
	v_pk_fma_f32 v[14:15], v[52:53], v[60:61], v[14:15] op_sel_hi:[1,0,1]
	v_pk_fma_f32 v[12:13], v[54:55], v[60:61], v[12:13] op_sel:[0,1,0]
	v_pk_fma_f32 v[10:11], v[52:53], v[60:61], v[10:11] op_sel:[0,1,0]
	v_pk_fma_f32 v[8:9], v[54:55], v[62:63], v[8:9] op_sel_hi:[1,0,1]
	v_pk_fma_f32 v[6:7], v[52:53], v[62:63], v[6:7] op_sel_hi:[1,0,1]
	v_pk_fma_f32 v[4:5], v[54:55], v[62:63], v[4:5] op_sel:[0,1,0]
	v_pk_fma_f32 v[2:3], v[52:53], v[62:63], v[2:3] op_sel:[0,1,0]
	v_add_u32_e32 v35, 0x840, v35
	s_cbranch_scc1 .LBB0_565
	s_waitcnt lgkmcnt(0)
	v_ashrrev_i32_e32 v34, 2, v34
	s_load_dwordx2 s[14:15], s[0:1], 0x88
	v_and_b32_e32 v34, -8, v34
	v_add_u32_e32 v37, s9, v34
	v_add_u32_e32 v34, s10, v37
	v_ashrrev_i32_e32 v35, 31, v34
	s_waitcnt lgkmcnt(0)
	v_lshl_add_u64 v[34:35], v[34:35], 2, s[14:15]
	global_load_dword v36, v[34:35], off
	global_load_dword v52, v[34:35], off offset:4
	global_load_dword v54, v[34:35], off offset:8
	global_load_dword v56, v[34:35], off offset:12
	global_load_dword v58, v[34:35], off offset:16
	global_load_dword v60, v[34:35], off offset:20
	global_load_dword v62, v[34:35], off offset:24
	global_load_dword v64, v[34:35], off offset:28
	s_ashr_i32 s9, s8, 31
	s_lshl_b64 s[8:9], s[8:9], 2
	s_add_u32 s8, s11, s8
	v_lshlrev_b32_e32 v0, 4, v0
	s_addc_u32 s9, s12, s9
	v_lshl_add_u64 v[38:39], s[8:9], 0, v[0:1]
	v_mad_i64_i32 v[40:41], s[8:9], v37, s61, v[38:39]
	s_add_i32 s13, s13, s98
	s_cmp_gt_i32 s13, s99
	s_waitcnt vmcnt(0)
	v_pk_add_f32 v[32:33], v[32:33], v[36:37] op_sel_hi:[1,0]
	v_pk_add_f32 v[30:31], v[30:31], v[36:37] op_sel_hi:[1,0]
	global_store_dwordx4 v[40:41], v[30:33], off
	s_nop 1
	v_pk_add_f32 v[28:29], v[28:29], v[52:53] op_sel_hi:[1,0]
	v_or_b32_e32 v30, 1, v37
	v_mad_i64_i32 v[30:31], s[8:9], v30, s61, v[38:39]
	v_pk_add_f32 v[26:27], v[26:27], v[52:53] op_sel_hi:[1,0]
	global_store_dwordx4 v[30:31], v[26:29], off
	s_nop 1
	v_pk_add_f32 v[24:25], v[24:25], v[54:55] op_sel_hi:[1,0]
	v_or_b32_e32 v26, 2, v37
	v_mad_i64_i32 v[26:27], s[8:9], v26, s61, v[38:39]
	v_pk_add_f32 v[22:23], v[22:23], v[54:55] op_sel_hi:[1,0]
	global_store_dwordx4 v[26:27], v[22:25], off
	s_nop 1
	v_pk_add_f32 v[20:21], v[20:21], v[56:57] op_sel_hi:[1,0]
	v_or_b32_e32 v22, 3, v37
	v_mad_i64_i32 v[22:23], s[8:9], v22, s61, v[38:39]
	v_pk_add_f32 v[18:19], v[18:19], v[56:57] op_sel_hi:[1,0]
	global_store_dwordx4 v[22:23], v[18:21], off
	s_nop 1
	v_pk_add_f32 v[16:17], v[16:17], v[58:59] op_sel_hi:[1,0]
	v_or_b32_e32 v18, 4, v37
	v_mad_i64_i32 v[18:19], s[8:9], v18, s61, v[38:39]
	v_pk_add_f32 v[14:15], v[14:15], v[58:59] op_sel_hi:[1,0]
	global_store_dwordx4 v[18:19], v[14:17], off
	s_nop 1
	v_pk_add_f32 v[12:13], v[12:13], v[60:61] op_sel_hi:[1,0]
	v_or_b32_e32 v14, 5, v37
	v_mad_i64_i32 v[14:15], s[8:9], v14, s61, v[38:39]
	v_pk_add_f32 v[10:11], v[10:11], v[60:61] op_sel_hi:[1,0]
	global_store_dwordx4 v[14:15], v[10:13], off
	s_nop 1
	v_pk_add_f32 v[8:9], v[8:9], v[62:63] op_sel_hi:[1,0]
	v_or_b32_e32 v10, 6, v37
	v_mad_i64_i32 v[10:11], s[8:9], v10, s61, v[38:39]
	v_pk_add_f32 v[6:7], v[6:7], v[62:63] op_sel_hi:[1,0]
	global_store_dwordx4 v[10:11], v[6:9], off
	s_nop 1
	v_pk_add_f32 v[4:5], v[4:5], v[64:65] op_sel_hi:[1,0]
	v_or_b32_e32 v6, 7, v37
	v_mad_i64_i32 v[6:7], s[8:9], v6, s61, v[38:39]
	v_pk_add_f32 v[2:3], v[2:3], v[64:65] op_sel_hi:[1,0]
	global_store_dwordx4 v[6:7], v[2:5], off
	s_nop 1
	s_barrier
	s_cbranch_scc0 .LBB0_564
